# DA context unit: map-0 pass moved onto the pipelined LDS ring loop (7-iteration loop, junk DMAs to dummy LDS); map-1 pass unchanged
# speedup vs baseline: 1.0013x; 1.0000x over previous
.LBB0_734:
	s_xor_b64 s[18:19], s[16:17], -1
	s_lshl_b32 s11, s10, 7
	v_mov_b32_e32 v0, v185
	v_mov_b32_e32 v4, v184
	s_add_u32 s12, s5, s11
	s_addc_u32 s13, s7, 0
	v_mov_b64_e32 v[2:3], s[12:13]
	v_lshlrev_b32_e32 v4, 3, v4
	v_mad_i64_i32 v[2:3], s[12:13], v0, s76, v[2:3]
	v_ashrrev_i32_e32 v5, 31, v4
	s_lshl_b32 s10, s10, 12
	v_readlane_b32 s11, v252, 35
	v_lshl_add_u64 v[2:3], v[4:5], 1, v[2:3]
	s_or_b32 s12, s10, s11
	s_mov_b32 s13, s56
	global_load_dwordx4 v[108:111], v[2:3], off
	global_load_dwordx4 v[104:107], v[2:3], off offset:32
	global_load_dwordx4 v[100:103], v[2:3], off offset:64
	global_load_dwordx4 v[96:99], v[2:3], off offset:96
	v_lshl_add_u64 v[2:3], v[152:153], 0, s[12:13]
	global_load_dwordx4 v[124:127], v[2:3], off
	global_load_dwordx4 v[120:123], v[2:3], off offset:1024
	global_load_dwordx4 v[116:119], v[2:3], off offset:2048
	global_load_dwordx4 v[112:115], v[2:3], off offset:3072
	v_mov_b32_e32 v14, v1
	v_mov_b32_e32 v15, v1
	s_add_u32 s24, s8, s12
	v_mov_b32_e32 v0, v1
	v_mov_b32_e32 v2, v1
	v_mov_b32_e32 v3, v1
	v_mov_b32_e32 v4, v1
	v_mov_b32_e32 v5, v1
	v_mov_b32_e32 v6, v1
	v_mov_b32_e32 v7, v1
	v_mov_b32_e32 v8, v1
	v_mov_b32_e32 v9, v1
	v_mov_b32_e32 v10, v1
	v_mov_b32_e32 v11, v1
	v_mov_b32_e32 v12, v1
	v_mov_b32_e32 v13, v1
	v_mov_b64_e32 v[30:31], v[14:15]
	v_mov_b64_e32 v[46:47], v[14:15]
	v_mov_b64_e32 v[62:63], v[14:15]
	v_mov_b64_e32 v[78:79], v[14:15]
	s_mov_b32 s10, 7
	s_addc_u32 s25, s9, 0
	v_mov_b32_e32 v187, 0
	v_mov_b32_e32 v188, 0xf149f2ca
	s_mov_b64 s[26:27], s[14:15]
	v_mov_b64_e32 v[28:29], v[12:13]
	v_mov_b64_e32 v[26:27], v[10:11]
	v_mov_b64_e32 v[24:25], v[8:9]
	v_mov_b64_e32 v[22:23], v[6:7]
	v_mov_b64_e32 v[20:21], v[4:5]
	v_mov_b64_e32 v[18:19], v[2:3]
	v_mov_b64_e32 v[16:17], v[0:1]
	v_mov_b64_e32 v[44:45], v[12:13]
	v_mov_b64_e32 v[42:43], v[10:11]
	v_mov_b64_e32 v[40:41], v[8:9]
	v_mov_b64_e32 v[38:39], v[6:7]
	v_mov_b64_e32 v[36:37], v[4:5]
	v_mov_b64_e32 v[34:35], v[2:3]
	v_mov_b64_e32 v[32:33], v[0:1]
	v_mov_b64_e32 v[60:61], v[12:13]
	v_mov_b64_e32 v[58:59], v[10:11]
	v_mov_b64_e32 v[56:57], v[8:9]
	v_mov_b64_e32 v[54:55], v[6:7]
	v_mov_b64_e32 v[52:53], v[4:5]
	v_mov_b64_e32 v[50:51], v[2:3]
	v_mov_b64_e32 v[48:49], v[0:1]
	v_mov_b64_e32 v[76:77], v[12:13]
	v_mov_b64_e32 v[74:75], v[10:11]
	v_mov_b64_e32 v[72:73], v[8:9]
	v_mov_b64_e32 v[70:71], v[6:7]
	v_mov_b64_e32 v[68:69], v[4:5]
	v_mov_b64_e32 v[66:67], v[2:3]
	v_mov_b64_e32 v[64:65], v[0:1]
	s_cmp_lg_u32 s16, 0
	s_cbranch_scc1 .Lmy_cx_ring
	s_branch .LBB0_736
.Lmy_cx_ring:
	s_waitcnt vmcnt(0)
	v_mfma_f32_32x32x16_bf16 v[80:95], v[124:127], v[108:111], 0
	v_mfma_f32_32x32x16_bf16 v[80:95], v[120:123], v[104:107], v[80:95]
	v_mfma_f32_32x32x16_bf16 v[80:95], v[116:119], v[100:103], v[80:95]
	v_mfma_f32_32x32x16_bf16 v[80:95], v[112:115], v[96:99], v[80:95]
	v_lshl_add_u64 v[14:15], v[152:153], 0, s[12:13]
	s_mov_b64 s[28:29], 0x10000
	s_mov_b32 s25, s53
	s_and_b32 s24, s25, 3
	s_lshl_b32 s24, s24, 11
	v_lshl_add_u64 v[14:15], s[28:29], 0, v[14:15]
	global_load_dwordx4 v[124:127], v[14:15], off
	global_load_dwordx4 v[120:123], v[14:15], off offset:1024
	global_load_dwordx4 v[116:119], v[14:15], off offset:2048
	global_load_dwordx4 v[112:115], v[14:15], off offset:3072
	s_cmp_lt_u32 s25, 4
	s_cbranch_scc0 .Lmy_cx_vsrc
	s_add_u32 s28, s24, 0x10000
	s_mov_b32 s29, 0
	v_mov_b32_e32 v244, 0x10000
	s_nop 0
	v_lshl_add_u64 v[242:243], s[28:29], 0, v[14:15]
	s_branch .Lmy_cx_srcdone
.Lmy_cx_vsrc:
	s_add_u32 s28, s24, 0xc500000
	s_mov_b32 s29, 0
	v_lshl_add_u64 v[242:243], s[14:15], 0, v[150:151]
	v_mov_b32_e32 v244, 0x2000
	s_nop 0
	v_lshl_add_u64 v[242:243], s[28:29], 0, v[242:243]
.Lmy_cx_srcdone:
	v_mov_b32_e32 v245, 0
	v_add_u32_e32 v246, 0x10000, v150
	v_mov_b32_e32 v247, v246
	s_lshl_b32 s24, s25, 11
	s_add_i32 s24, s24, 0x10000
	s_mov_b32 m0, s24
	s_nop 0
	global_load_lds_dwordx4 v[242:243], off
	global_load_lds_dwordx4 v[242:243], off offset:1024
	v_lshl_add_u64 v[242:243], v[244:245], 0, v[242:243]
	s_add_i32 m0, s24, 0x4000
	s_nop 0
	global_load_lds_dwordx4 v[242:243], off
	global_load_lds_dwordx4 v[242:243], off offset:1024
	v_lshl_add_u64 v[242:243], v[244:245], 0, v[242:243]
	s_add_i32 m0, s24, 0x8000
	s_nop 0
	global_load_lds_dwordx4 v[242:243], off
	global_load_lds_dwordx4 v[242:243], off offset:1024
	v_lshl_add_u64 v[242:243], v[244:245], 0, v[242:243]
	s_add_i32 s24, s24, 0xc000
	s_lshr_b32 s29, s25, 2
	s_mov_b32 s25, 0
	s_mov_b32 s13, 7
	s_waitcnt vmcnt(4)
	s_barrier
.Lmy_cx_loop2:
	v_add_u32_e32 v248, s25, v246
	v_add_u32_e32 v249, s25, v247
	ds_read_b128 v[144:147], v248 offset:8192
	ds_read_b128 v[136:139], v248 offset:10240
	ds_read_b128 v[132:135], v248 offset:12288
	ds_read_b128 v[2:5], v248 offset:14336
	ds_read_b128 v[128:131], v248 offset:9216
	ds_read_b128 v[140:143], v248 offset:11264
	ds_read_b128 v[10:13], v248 offset:13312
	ds_read_b128 v[6:9], v248 offset:15360
	v_max3_f32 v14, v80, v81, v82
	v_max3_f32 v15, v83, v84, v85
	v_max3_f32 v209, v86, v87, v88
	v_max3_f32 v212, v89, v90, v91
	v_max3_f32 v14, v14, v92, v93
	v_max3_f32 v15, v15, v94, v95
	v_max3_f32 v14, v14, v15, v209
	v_max_f32_e32 v14, v14, v212
	v_mov_b32_e32 v15, v14
	s_sub_i32 s28, 4, s29
	s_cmp_gt_u32 s13, s28
	s_cselect_b32 m0, s24, 0x20000
	s_add_i32 s28, s28, 1
	s_cmp_gt_u32 s13, s28
	s_cselect_b32 s28, -1, 0
	v_permlane32_swap_b32_e32 v14, v15
	s_add_i32 s24, s24, 0x4000
	s_and_b32 s24, s24, 0xffff
	v_max_f32_e32 v14, v14, v15
	v_add_f32_e32 v15, 0x41000000, v188
	v_cmp_gt_f32_e32 vcc, v14, v15
	s_cbranch_vccz .Lmy_cx_nors_a
	v_max_f32_e32 v15, v188, v14
	v_sub_f32_e32 v14, v188, v15
	v_exp_f32_e32 v14, v14
	v_mov_b32_e32 v188, v15
	s_nop 0
	v_mul_f32_e32 v187, v187, v14
	v_pk_mul_f32 v[78:79], v[78:79], v[14:15] op_sel_hi:[1,0]
	v_pk_mul_f32 v[76:77], v[76:77], v[14:15] op_sel_hi:[1,0]
	v_pk_mul_f32 v[74:75], v[74:75], v[14:15] op_sel_hi:[1,0]
	v_pk_mul_f32 v[72:73], v[72:73], v[14:15] op_sel_hi:[1,0]
	v_pk_mul_f32 v[70:71], v[70:71], v[14:15] op_sel_hi:[1,0]
	v_pk_mul_f32 v[68:69], v[68:69], v[14:15] op_sel_hi:[1,0]
	v_pk_mul_f32 v[66:67], v[66:67], v[14:15] op_sel_hi:[1,0]
	v_pk_mul_f32 v[64:65], v[64:65], v[14:15] op_sel_hi:[1,0]
	v_pk_mul_f32 v[62:63], v[62:63], v[14:15] op_sel_hi:[1,0]
	v_pk_mul_f32 v[60:61], v[60:61], v[14:15] op_sel_hi:[1,0]
	v_pk_mul_f32 v[58:59], v[58:59], v[14:15] op_sel_hi:[1,0]
	v_pk_mul_f32 v[56:57], v[56:57], v[14:15] op_sel_hi:[1,0]
	v_pk_mul_f32 v[54:55], v[54:55], v[14:15] op_sel_hi:[1,0]
	v_pk_mul_f32 v[52:53], v[52:53], v[14:15] op_sel_hi:[1,0]
	v_pk_mul_f32 v[50:51], v[50:51], v[14:15] op_sel_hi:[1,0]
	v_pk_mul_f32 v[48:49], v[48:49], v[14:15] op_sel_hi:[1,0]
	v_pk_mul_f32 v[46:47], v[46:47], v[14:15] op_sel_hi:[1,0]
	v_pk_mul_f32 v[44:45], v[44:45], v[14:15] op_sel_hi:[1,0]
	v_pk_mul_f32 v[42:43], v[42:43], v[14:15] op_sel_hi:[1,0]
	v_pk_mul_f32 v[40:41], v[40:41], v[14:15] op_sel_hi:[1,0]
	v_pk_mul_f32 v[38:39], v[38:39], v[14:15] op_sel_hi:[1,0]
	v_pk_mul_f32 v[36:37], v[36:37], v[14:15] op_sel_hi:[1,0]
	v_pk_mul_f32 v[34:35], v[34:35], v[14:15] op_sel_hi:[1,0]
	v_pk_mul_f32 v[32:33], v[32:33], v[14:15] op_sel_hi:[1,0]
	v_pk_mul_f32 v[30:31], v[30:31], v[14:15] op_sel_hi:[1,0]
	v_pk_mul_f32 v[28:29], v[28:29], v[14:15] op_sel_hi:[1,0]
	v_pk_mul_f32 v[26:27], v[26:27], v[14:15] op_sel_hi:[1,0]
	v_pk_mul_f32 v[24:25], v[24:25], v[14:15] op_sel_hi:[1,0]
	v_pk_mul_f32 v[22:23], v[22:23], v[14:15] op_sel_hi:[1,0]
	v_pk_mul_f32 v[20:21], v[20:21], v[14:15] op_sel_hi:[1,0]
	v_pk_mul_f32 v[18:19], v[18:19], v[14:15] op_sel_hi:[1,0]
	v_pk_mul_f32 v[16:17], v[16:17], v[14:15] op_sel_hi:[1,0]
.Lmy_cx_nors_a:
	v_sub_f32_e32 v14, v80, v188
	v_exp_f32_e32 v14, v14
	v_mfma_f32_32x32x16_bf16 v[218:233], v[124:127], v[108:111], 0
	v_sub_f32_e32 v80, v81, v188
	v_exp_f32_e32 v80, v80
	v_sub_f32_e32 v81, v82, v188
	v_exp_f32_e32 v81, v81
	v_sub_f32_e32 v82, v83, v188
	v_mfma_f32_32x32x16_bf16 v[218:233], v[120:123], v[104:107], v[218:233]
	v_exp_f32_e32 v82, v82
	v_sub_f32_e32 v83, v84, v188
	v_sub_f32_e32 v84, v85, v188
	v_sub_f32_e32 v85, v86, v188
	v_sub_f32_e32 v86, v87, v188
	v_add_f32_e32 v15, 0, v14
	global_load_lds_dwordx4 v[242:243], off
	global_load_lds_dwordx4 v[242:243], off offset:1024
	v_mfma_f32_32x32x16_bf16 v[218:233], v[116:119], v[100:103], v[218:233]
	v_exp_f32_e32 v83, v83
	v_exp_f32_e32 v84, v84
	v_exp_f32_e32 v85, v85
	v_and_b32_e32 v244, s28, v244
	v_mfma_f32_32x32x16_bf16 v[218:233], v[112:115], v[96:99], v[218:233]
	v_exp_f32_e32 v86, v86
	v_lshl_add_u64 v[242:243], v[244:245], 0, v[242:243]
	s_or_b32 s24, s24, 0x10000
	ds_read_b128 v[124:127], v249
	ds_read_b128 v[120:123], v249 offset:1024
	ds_read_b128 v[116:119], v249 offset:2048
	ds_read_b128 v[112:115], v249 offset:3072
	s_add_i32 s25, s25, 0x4000
	s_and_b32 s25, s25, 0xc000
	v_add_f32_e32 v15, v80, v15
	v_add_f32_e32 v15, v81, v15
	v_add_f32_e32 v15, v82, v15
	v_add_f32_e32 v15, v83, v15
	v_cvt_pk_bf16_f32 v80, v14, v80
	v_cvt_pk_bf16_f32 v81, v81, v82
	v_cvt_pk_bf16_f32 v82, v83, v84
	v_cvt_pk_bf16_f32 v83, v85, v86
	v_sub_f32_e32 v87, v88, v188
	v_sub_f32_e32 v88, v89, v188
	s_waitcnt lgkmcnt(4)
	v_mfma_f32_32x32x16_bf16 v[64:79], v[144:147], v[80:83], v[64:79]
	v_sub_f32_e32 v89, v90, v188
	v_sub_f32_e32 v90, v91, v188
	v_sub_f32_e32 v91, v92, v188
	v_exp_f32_e32 v87, v87
	v_exp_f32_e32 v88, v88
	v_mfma_f32_32x32x16_bf16 v[48:63], v[136:139], v[80:83], v[48:63]
	v_sub_f32_e32 v92, v93, v188
	v_sub_f32_e32 v93, v94, v188
	v_sub_f32_e32 v94, v95, v188
	v_exp_f32_e32 v89, v89
	v_exp_f32_e32 v90, v90
	v_mfma_f32_32x32x16_bf16 v[32:47], v[132:135], v[80:83], v[32:47]
	v_exp_f32_e32 v91, v91
	v_exp_f32_e32 v92, v92
	v_exp_f32_e32 v93, v93
	v_exp_f32_e32 v94, v94
	v_mfma_f32_32x32x16_bf16 v[16:31], v[2:5], v[80:83], v[16:31]
	s_cmp_eq_u32 s29, 0
	s_cbranch_scc1 .Lmy_cx_nbm_a
	s_waitcnt vmcnt(4) lgkmcnt(0)
	s_barrier
.Lmy_cx_nbm_a:
	v_add_f32_e32 v15, v84, v15
	v_add_f32_e32 v15, v85, v15
	v_add_f32_e32 v15, v86, v15
	v_add_f32_e32 v15, v87, v15
	v_cvt_pk_bf16_f32 v84, v87, v88
	v_cvt_pk_bf16_f32 v85, v89, v90
	v_cvt_pk_bf16_f32 v86, v91, v92
	v_cvt_pk_bf16_f32 v87, v93, v94
	v_add_f32_e32 v15, v88, v15
	v_add_f32_e32 v15, v89, v15
	v_mfma_f32_32x32x16_bf16 v[64:79], v[128:131], v[84:87], v[64:79]
	v_add_f32_e32 v15, v90, v15
	v_add_f32_e32 v15, v91, v15
	s_add_i32 s13, s13, -1
	v_mfma_f32_32x32x16_bf16 v[48:63], v[140:143], v[84:87], v[48:63]
	v_add_f32_e32 v15, v92, v15
	v_add_f32_e32 v15, v93, v15
	v_mfma_f32_32x32x16_bf16 v[32:47], v[10:13], v[84:87], v[32:47]
	v_add_f32_e32 v15, v94, v15
	v_add_f32_e32 v187, v187, v15
	v_mfma_f32_32x32x16_bf16 v[16:31], v[6:9], v[84:87], v[16:31]
	s_cmp_lg_u32 s29, 0
	s_cbranch_scc1 .Lmy_cx_nbe_a
	s_waitcnt vmcnt(4) lgkmcnt(0)
	s_barrier
.Lmy_cx_nbe_a:
	v_add_u32_e32 v248, s25, v246
	v_add_u32_e32 v249, s25, v247
	ds_read_b128 v[144:147], v248 offset:8192
	ds_read_b128 v[136:139], v248 offset:10240
	ds_read_b128 v[132:135], v248 offset:12288
	ds_read_b128 v[2:5], v248 offset:14336
	ds_read_b128 v[128:131], v248 offset:9216
	ds_read_b128 v[140:143], v248 offset:11264
	ds_read_b128 v[10:13], v248 offset:13312
	ds_read_b128 v[6:9], v248 offset:15360
	v_max3_f32 v14, v218, v219, v220
	v_max3_f32 v15, v221, v222, v223
	v_max3_f32 v209, v224, v225, v226
	v_max3_f32 v212, v227, v228, v229
	v_max3_f32 v14, v14, v230, v231
	v_max3_f32 v15, v15, v232, v233
	v_max3_f32 v14, v14, v15, v209
	v_max_f32_e32 v14, v14, v212
	v_mov_b32_e32 v15, v14
	s_sub_i32 s28, 4, s29
	s_cmp_gt_u32 s13, s28
	s_cselect_b32 m0, s24, 0x20000
	s_add_i32 s28, s28, 1
	s_cmp_gt_u32 s13, s28
	s_cselect_b32 s28, -1, 0
	v_permlane32_swap_b32_e32 v14, v15
	s_add_i32 s24, s24, 0x4000
	s_and_b32 s24, s24, 0xffff
	v_max_f32_e32 v14, v14, v15
	v_add_f32_e32 v15, 0x41000000, v188
	v_cmp_gt_f32_e32 vcc, v14, v15
	s_cbranch_vccz .Lmy_cx_nors_b
	v_max_f32_e32 v15, v188, v14
	v_sub_f32_e32 v14, v188, v15
	v_exp_f32_e32 v14, v14
	v_mov_b32_e32 v188, v15
	s_nop 0
	v_mul_f32_e32 v187, v187, v14
	v_pk_mul_f32 v[78:79], v[78:79], v[14:15] op_sel_hi:[1,0]
	v_pk_mul_f32 v[76:77], v[76:77], v[14:15] op_sel_hi:[1,0]
	v_pk_mul_f32 v[74:75], v[74:75], v[14:15] op_sel_hi:[1,0]
	v_pk_mul_f32 v[72:73], v[72:73], v[14:15] op_sel_hi:[1,0]
	v_pk_mul_f32 v[70:71], v[70:71], v[14:15] op_sel_hi:[1,0]
	v_pk_mul_f32 v[68:69], v[68:69], v[14:15] op_sel_hi:[1,0]
	v_pk_mul_f32 v[66:67], v[66:67], v[14:15] op_sel_hi:[1,0]
	v_pk_mul_f32 v[64:65], v[64:65], v[14:15] op_sel_hi:[1,0]
	v_pk_mul_f32 v[62:63], v[62:63], v[14:15] op_sel_hi:[1,0]
	v_pk_mul_f32 v[60:61], v[60:61], v[14:15] op_sel_hi:[1,0]
	v_pk_mul_f32 v[58:59], v[58:59], v[14:15] op_sel_hi:[1,0]
	v_pk_mul_f32 v[56:57], v[56:57], v[14:15] op_sel_hi:[1,0]
	v_pk_mul_f32 v[54:55], v[54:55], v[14:15] op_sel_hi:[1,0]
	v_pk_mul_f32 v[52:53], v[52:53], v[14:15] op_sel_hi:[1,0]
	v_pk_mul_f32 v[50:51], v[50:51], v[14:15] op_sel_hi:[1,0]
	v_pk_mul_f32 v[48:49], v[48:49], v[14:15] op_sel_hi:[1,0]
	v_pk_mul_f32 v[46:47], v[46:47], v[14:15] op_sel_hi:[1,0]
	v_pk_mul_f32 v[44:45], v[44:45], v[14:15] op_sel_hi:[1,0]
	v_pk_mul_f32 v[42:43], v[42:43], v[14:15] op_sel_hi:[1,0]
	v_pk_mul_f32 v[40:41], v[40:41], v[14:15] op_sel_hi:[1,0]
	v_pk_mul_f32 v[38:39], v[38:39], v[14:15] op_sel_hi:[1,0]
	v_pk_mul_f32 v[36:37], v[36:37], v[14:15] op_sel_hi:[1,0]
	v_pk_mul_f32 v[34:35], v[34:35], v[14:15] op_sel_hi:[1,0]
	v_pk_mul_f32 v[32:33], v[32:33], v[14:15] op_sel_hi:[1,0]
	v_pk_mul_f32 v[30:31], v[30:31], v[14:15] op_sel_hi:[1,0]
	v_pk_mul_f32 v[28:29], v[28:29], v[14:15] op_sel_hi:[1,0]
	v_pk_mul_f32 v[26:27], v[26:27], v[14:15] op_sel_hi:[1,0]
	v_pk_mul_f32 v[24:25], v[24:25], v[14:15] op_sel_hi:[1,0]
	v_pk_mul_f32 v[22:23], v[22:23], v[14:15] op_sel_hi:[1,0]
	v_pk_mul_f32 v[20:21], v[20:21], v[14:15] op_sel_hi:[1,0]
	v_pk_mul_f32 v[18:19], v[18:19], v[14:15] op_sel_hi:[1,0]
	v_pk_mul_f32 v[16:17], v[16:17], v[14:15] op_sel_hi:[1,0]
.Lmy_cx_nors_b:
	v_sub_f32_e32 v14, v218, v188
	v_exp_f32_e32 v14, v14
	v_mfma_f32_32x32x16_bf16 v[80:95], v[124:127], v[108:111], 0
	v_sub_f32_e32 v218, v219, v188
	v_exp_f32_e32 v218, v218
	v_sub_f32_e32 v219, v220, v188
	v_exp_f32_e32 v219, v219
	v_sub_f32_e32 v220, v221, v188
	v_mfma_f32_32x32x16_bf16 v[80:95], v[120:123], v[104:107], v[80:95]
	v_exp_f32_e32 v220, v220
	v_sub_f32_e32 v221, v222, v188
	v_sub_f32_e32 v222, v223, v188
	v_sub_f32_e32 v223, v224, v188
	v_sub_f32_e32 v224, v225, v188
	v_add_f32_e32 v15, 0, v14
	global_load_lds_dwordx4 v[242:243], off
	global_load_lds_dwordx4 v[242:243], off offset:1024
	v_mfma_f32_32x32x16_bf16 v[80:95], v[116:119], v[100:103], v[80:95]
	v_exp_f32_e32 v221, v221
	v_exp_f32_e32 v222, v222
	v_exp_f32_e32 v223, v223
	v_and_b32_e32 v244, s28, v244
	v_mfma_f32_32x32x16_bf16 v[80:95], v[112:115], v[96:99], v[80:95]
	v_exp_f32_e32 v224, v224
	v_lshl_add_u64 v[242:243], v[244:245], 0, v[242:243]
	s_or_b32 s24, s24, 0x10000
	ds_read_b128 v[124:127], v249
	ds_read_b128 v[120:123], v249 offset:1024
	ds_read_b128 v[116:119], v249 offset:2048
	ds_read_b128 v[112:115], v249 offset:3072
	s_add_i32 s25, s25, 0x4000
	s_and_b32 s25, s25, 0xc000
	v_add_f32_e32 v15, v218, v15
	v_add_f32_e32 v15, v219, v15
	v_add_f32_e32 v15, v220, v15
	v_add_f32_e32 v15, v221, v15
	v_cvt_pk_bf16_f32 v218, v14, v218
	v_cvt_pk_bf16_f32 v219, v219, v220
	v_cvt_pk_bf16_f32 v220, v221, v222
	v_cvt_pk_bf16_f32 v221, v223, v224
	v_sub_f32_e32 v225, v226, v188
	v_sub_f32_e32 v226, v227, v188
	s_waitcnt lgkmcnt(4)
	v_mfma_f32_32x32x16_bf16 v[64:79], v[144:147], v[218:221], v[64:79]
	v_sub_f32_e32 v227, v228, v188
	v_sub_f32_e32 v228, v229, v188
	v_sub_f32_e32 v229, v230, v188
	v_exp_f32_e32 v225, v225
	v_exp_f32_e32 v226, v226
	v_mfma_f32_32x32x16_bf16 v[48:63], v[136:139], v[218:221], v[48:63]
	v_sub_f32_e32 v230, v231, v188
	v_sub_f32_e32 v231, v232, v188
	v_sub_f32_e32 v232, v233, v188
	v_exp_f32_e32 v227, v227
	v_exp_f32_e32 v228, v228
	v_mfma_f32_32x32x16_bf16 v[32:47], v[132:135], v[218:221], v[32:47]
	v_exp_f32_e32 v229, v229
	v_exp_f32_e32 v230, v230
	v_exp_f32_e32 v231, v231
	v_exp_f32_e32 v232, v232
	v_mfma_f32_32x32x16_bf16 v[16:31], v[2:5], v[218:221], v[16:31]
	s_cmp_eq_u32 s29, 0
	s_cbranch_scc1 .Lmy_cx_nbm_b
	s_waitcnt vmcnt(4) lgkmcnt(0)
	s_barrier
.Lmy_cx_nbm_b:
	v_add_f32_e32 v15, v222, v15
	v_add_f32_e32 v15, v223, v15
	v_add_f32_e32 v15, v224, v15
	v_add_f32_e32 v15, v225, v15
	v_cvt_pk_bf16_f32 v222, v225, v226
	v_cvt_pk_bf16_f32 v223, v227, v228
	v_cvt_pk_bf16_f32 v224, v229, v230
	v_cvt_pk_bf16_f32 v225, v231, v232
	v_add_f32_e32 v15, v226, v15
	v_add_f32_e32 v15, v227, v15
	v_mfma_f32_32x32x16_bf16 v[64:79], v[128:131], v[222:225], v[64:79]
	v_add_f32_e32 v15, v228, v15
	v_add_f32_e32 v15, v229, v15
	s_add_i32 s13, s13, -1
	v_mfma_f32_32x32x16_bf16 v[48:63], v[140:143], v[222:225], v[48:63]
	v_add_f32_e32 v15, v230, v15
	v_add_f32_e32 v15, v231, v15
	v_mfma_f32_32x32x16_bf16 v[32:47], v[10:13], v[222:225], v[32:47]
	v_add_f32_e32 v15, v232, v15
	v_add_f32_e32 v187, v187, v15
	v_mfma_f32_32x32x16_bf16 v[16:31], v[6:9], v[222:225], v[16:31]
	s_cmp_lg_u32 s29, 0
	s_cbranch_scc1 .Lmy_cx_nbe_b
	s_waitcnt vmcnt(4) lgkmcnt(0)
	s_barrier
.Lmy_cx_nbe_b:
	s_cmp_gt_u32 s13, 1
	s_cbranch_scc1 .Lmy_cx_loop2
	v_add_u32_e32 v248, s25, v246
	v_add_u32_e32 v249, s25, v247
	ds_read_b128 v[144:147], v248 offset:8192
	ds_read_b128 v[136:139], v248 offset:10240
	ds_read_b128 v[132:135], v248 offset:12288
	ds_read_b128 v[2:5], v248 offset:14336
	ds_read_b128 v[128:131], v248 offset:9216
	ds_read_b128 v[140:143], v248 offset:11264
	ds_read_b128 v[10:13], v248 offset:13312
	ds_read_b128 v[6:9], v248 offset:15360
	v_max3_f32 v14, v80, v81, v82
	v_max3_f32 v15, v83, v84, v85
	v_max3_f32 v209, v86, v87, v88
	v_max3_f32 v212, v89, v90, v91
	v_max3_f32 v14, v14, v92, v93
	v_max3_f32 v15, v15, v94, v95
	v_max3_f32 v14, v14, v15, v209
	v_max_f32_e32 v14, v14, v212
	v_mov_b32_e32 v15, v14
	s_sub_i32 s28, 4, s29
	s_cmp_gt_u32 s13, s28
	s_cselect_b32 m0, s24, 0x20000
	s_add_i32 s28, s28, 1
	s_cmp_gt_u32 s13, s28
	s_cselect_b32 s28, -1, 0
	v_permlane32_swap_b32_e32 v14, v15
	s_add_i32 s24, s24, 0x4000
	s_and_b32 s24, s24, 0xffff
	v_max_f32_e32 v14, v14, v15
	v_add_f32_e32 v15, 0x41000000, v188
	v_cmp_gt_f32_e32 vcc, v14, v15
	s_cbranch_vccz .Lmy_cx_nors_t
	v_max_f32_e32 v15, v188, v14
	v_sub_f32_e32 v14, v188, v15
	v_exp_f32_e32 v14, v14
	v_mov_b32_e32 v188, v15
	s_nop 0
	v_mul_f32_e32 v187, v187, v14
	v_pk_mul_f32 v[78:79], v[78:79], v[14:15] op_sel_hi:[1,0]
	v_pk_mul_f32 v[76:77], v[76:77], v[14:15] op_sel_hi:[1,0]
	v_pk_mul_f32 v[74:75], v[74:75], v[14:15] op_sel_hi:[1,0]
	v_pk_mul_f32 v[72:73], v[72:73], v[14:15] op_sel_hi:[1,0]
	v_pk_mul_f32 v[70:71], v[70:71], v[14:15] op_sel_hi:[1,0]
	v_pk_mul_f32 v[68:69], v[68:69], v[14:15] op_sel_hi:[1,0]
	v_pk_mul_f32 v[66:67], v[66:67], v[14:15] op_sel_hi:[1,0]
	v_pk_mul_f32 v[64:65], v[64:65], v[14:15] op_sel_hi:[1,0]
	v_pk_mul_f32 v[62:63], v[62:63], v[14:15] op_sel_hi:[1,0]
	v_pk_mul_f32 v[60:61], v[60:61], v[14:15] op_sel_hi:[1,0]
	v_pk_mul_f32 v[58:59], v[58:59], v[14:15] op_sel_hi:[1,0]
	v_pk_mul_f32 v[56:57], v[56:57], v[14:15] op_sel_hi:[1,0]
	v_pk_mul_f32 v[54:55], v[54:55], v[14:15] op_sel_hi:[1,0]
	v_pk_mul_f32 v[52:53], v[52:53], v[14:15] op_sel_hi:[1,0]
	v_pk_mul_f32 v[50:51], v[50:51], v[14:15] op_sel_hi:[1,0]
	v_pk_mul_f32 v[48:49], v[48:49], v[14:15] op_sel_hi:[1,0]
	v_pk_mul_f32 v[46:47], v[46:47], v[14:15] op_sel_hi:[1,0]
	v_pk_mul_f32 v[44:45], v[44:45], v[14:15] op_sel_hi:[1,0]
	v_pk_mul_f32 v[42:43], v[42:43], v[14:15] op_sel_hi:[1,0]
	v_pk_mul_f32 v[40:41], v[40:41], v[14:15] op_sel_hi:[1,0]
	v_pk_mul_f32 v[38:39], v[38:39], v[14:15] op_sel_hi:[1,0]
	v_pk_mul_f32 v[36:37], v[36:37], v[14:15] op_sel_hi:[1,0]
	v_pk_mul_f32 v[34:35], v[34:35], v[14:15] op_sel_hi:[1,0]
	v_pk_mul_f32 v[32:33], v[32:33], v[14:15] op_sel_hi:[1,0]
	v_pk_mul_f32 v[30:31], v[30:31], v[14:15] op_sel_hi:[1,0]
	v_pk_mul_f32 v[28:29], v[28:29], v[14:15] op_sel_hi:[1,0]
	v_pk_mul_f32 v[26:27], v[26:27], v[14:15] op_sel_hi:[1,0]
	v_pk_mul_f32 v[24:25], v[24:25], v[14:15] op_sel_hi:[1,0]
	v_pk_mul_f32 v[22:23], v[22:23], v[14:15] op_sel_hi:[1,0]
	v_pk_mul_f32 v[20:21], v[20:21], v[14:15] op_sel_hi:[1,0]
	v_pk_mul_f32 v[18:19], v[18:19], v[14:15] op_sel_hi:[1,0]
	v_pk_mul_f32 v[16:17], v[16:17], v[14:15] op_sel_hi:[1,0]
.Lmy_cx_nors_t:
	v_sub_f32_e32 v14, v80, v188
	v_exp_f32_e32 v14, v14
	v_mfma_f32_32x32x16_bf16 v[218:233], v[124:127], v[108:111], 0
	v_sub_f32_e32 v80, v81, v188
	v_exp_f32_e32 v80, v80
	v_sub_f32_e32 v81, v82, v188
	v_exp_f32_e32 v81, v81
	v_sub_f32_e32 v82, v83, v188
	v_mfma_f32_32x32x16_bf16 v[218:233], v[120:123], v[104:107], v[218:233]
	v_exp_f32_e32 v82, v82
	v_sub_f32_e32 v83, v84, v188
	v_sub_f32_e32 v84, v85, v188
	v_sub_f32_e32 v85, v86, v188
	v_sub_f32_e32 v86, v87, v188
	v_add_f32_e32 v15, 0, v14
	global_load_lds_dwordx4 v[242:243], off
	global_load_lds_dwordx4 v[242:243], off offset:1024
	v_mfma_f32_32x32x16_bf16 v[218:233], v[116:119], v[100:103], v[218:233]
	v_exp_f32_e32 v83, v83
	v_exp_f32_e32 v84, v84
	v_exp_f32_e32 v85, v85
	v_and_b32_e32 v244, s28, v244
	v_mfma_f32_32x32x16_bf16 v[218:233], v[112:115], v[96:99], v[218:233]
	v_exp_f32_e32 v86, v86
	v_lshl_add_u64 v[242:243], v[244:245], 0, v[242:243]
	s_or_b32 s24, s24, 0x10000
	s_add_i32 s25, s25, 0x4000
	s_and_b32 s25, s25, 0xc000
	v_add_f32_e32 v15, v80, v15
	v_add_f32_e32 v15, v81, v15
	v_add_f32_e32 v15, v82, v15
	v_add_f32_e32 v15, v83, v15
	v_cvt_pk_bf16_f32 v80, v14, v80
	v_cvt_pk_bf16_f32 v81, v81, v82
	v_cvt_pk_bf16_f32 v82, v83, v84
	v_cvt_pk_bf16_f32 v83, v85, v86
	v_sub_f32_e32 v87, v88, v188
	v_sub_f32_e32 v88, v89, v188
	s_waitcnt lgkmcnt(0)
	v_mfma_f32_32x32x16_bf16 v[64:79], v[144:147], v[80:83], v[64:79]
	v_sub_f32_e32 v89, v90, v188
	v_sub_f32_e32 v90, v91, v188
	v_sub_f32_e32 v91, v92, v188
	v_exp_f32_e32 v87, v87
	v_exp_f32_e32 v88, v88
	v_mfma_f32_32x32x16_bf16 v[48:63], v[136:139], v[80:83], v[48:63]
	v_sub_f32_e32 v92, v93, v188
	v_sub_f32_e32 v93, v94, v188
	v_sub_f32_e32 v94, v95, v188
	v_exp_f32_e32 v89, v89
	v_exp_f32_e32 v90, v90
	v_mfma_f32_32x32x16_bf16 v[32:47], v[132:135], v[80:83], v[32:47]
	v_exp_f32_e32 v91, v91
	v_exp_f32_e32 v92, v92
	v_exp_f32_e32 v93, v93
	v_exp_f32_e32 v94, v94
	v_mfma_f32_32x32x16_bf16 v[16:31], v[2:5], v[80:83], v[16:31]
	s_cmp_eq_u32 s29, 0
	s_cbranch_scc1 .Lmy_cx_nbm_t
	s_waitcnt vmcnt(4) lgkmcnt(0)
	s_barrier

.Lmy_cx_nbe_t:
	s_mov_b32 s10, 0
	s_branch .LBB0_738
